# v30 + all small edits together: header shift/and division, GEMM4a SGPR-base staging, band-loop per-wave mask skip, static priority for attention waves 4-7, no K-loop priority toggles
# speedup vs baseline: 1.0062x; 1.0006x over previous
.LBB0_743:
	s_ashr_i32 s35, s34, 31
	s_lshl_b64 s[36:37], s[34:35], 17
	s_add_u32 s36, s13, s36
	s_addc_u32 s37, s22, s37
	s_and_b64 s[38:39], s[4:5], exec
	s_cselect_b32 s35, s37, s43
	s_cselect_b32 s82, s36, s42
	s_ashr_i32 s31, s30, 31
	s_lshl_b64 s[38:39], s[30:31], 17
	s_add_u32 s38, s23, s38
	s_addc_u32 s39, s58, s39
	s_and_b64 s[44:45], s[4:5], exec
	s_cselect_b32 s31, s39, s41
	s_cselect_b32 s83, s38, s40
	s_mov_b64 s[48:49], 0
	s_mov_b64 s[44:45], -1
	s_mov_b64 s[46:47], 0
	s_add_u32 s54, s42, s48
	s_addc_u32 s55, s43, s49
	s_add_u32 s52, s54, 0x100
	s_addc_u32 s53, s55, 0
	s_and_b64 s[50:51], s[46:47], exec
	s_cselect_b32 s51, s35, s53
	s_cselect_b32 s50, s82, s52
	s_add_u32 s48, s40, s48
	s_addc_u32 s49, s41, s49
	s_add_u32 s48, s48, 0x100
	s_addc_u32 s49, s49, 0
	s_and_b64 s[46:47], s[46:47], exec
	s_cselect_b32 s53, s31, s49
	s_cselect_b32 s52, s83, s48
	s_cselect_b32 s98, 1, 0
	s_add_u32 s56, s54, 0x10080
	ds_read_b128 v[150:153], v144
	ds_read_b128 v[154:157], v144 offset:1024
	ds_read_b128 v[158:161], v144 offset:2048
	ds_read_b128 v[162:165], v144 offset:3072
	ds_read_b128 v[166:169], v145
	ds_read_b128 v[170:173], v145 offset:1024
	ds_read_b128 v[174:177], v145 offset:2048
	ds_read_b128 v[178:181], v145 offset:3072
	s_addc_u32 s57, s55, 0
	s_add_i32 s93, s74, s60
	s_add_i32 m0, s61, 0xc000
	s_add_i32 s94, s61, 0xe000
	s_add_i32 s90, s93, 0x2000
	s_add_u32 s54, s52, 0x10000
	s_addc_u32 s55, s53, 0
	s_add_i32 s92, s75, s60
	s_add_i32 s91, s92, 0x2000
	s_add_i32 s89, 0, 0x18000
	s_add_i32 s88, 0, 0x1c000
	s_add_u32 s48, s50, 0x10000
	s_addc_u32 s49, s51, 0
	s_add_i32 s87, s89, s60
	s_add_i32 s85, s87, 0x2000
	s_add_u32 s46, s52, 0x10080
	s_addc_u32 s47, s53, 0
	s_add_i32 s86, s88, s60
	s_add_i32 s84, s86, 0x2000
	ds_read_b128 v[182:185], v146
	ds_read_b128 v[186:189], v146 offset:1024
	ds_read_b128 v[190:193], v146 offset:2048
	ds_read_b128 v[194:197], v146 offset:3072
	ds_read_b128 v[198:201], v146 offset:4096
	ds_read_b128 v[202:205], v146 offset:5120
	ds_read_b128 v[206:209], v146 offset:6144
	ds_read_b128 v[210:213], v146 offset:7168
	global_load_lds_dwordx4 v130, s[56:57]
	s_mov_b32 m0, s94
	s_nop 0
	global_load_lds_dwordx4 v128, s[56:57]
	s_waitcnt vmcnt(8)
	s_waitcnt lgkmcnt(0)
	s_cmp_lg_u32 s98, 0
	s_cbranch_scc0 .Lkv_nopf_pk
	v_lshl_add_u32 v138, s18, 8, v141
	v_ashrrev_i32_e32 v139, 31, v138
	v_lshl_add_u64 v[138:139], v[138:139], 4, s[14:15]
	global_load_dwordx4 v[222:225], v[138:139], off
	global_load_dwordx4 v[226:229], v[138:139], off offset:256
	global_load_dwordx4 v[230:233], v[138:139], off offset:512
	global_load_dwordx4 v[234:237], v[138:139], off offset:768
	global_load_dwordx4 v[238:241], v[138:139], off offset:2048
	global_load_dwordx4 v[242:245], v[138:139], off offset:2304
	global_load_dwordx4 v[248:251], v[138:139], off offset:2560
	global_load_dwordx4 v[252:255], v[138:139], off offset:2816
.Lkv_nopf_pk:
	s_barrier
	v_mfma_f32_16x16x32_bf16 v[124:127], v[150:153], v[182:185], 0
	v_mfma_f32_16x16x32_bf16 v[120:123], v[158:161], v[182:185], 0
	v_mfma_f32_16x16x32_bf16 v[108:111], v[150:153], v[190:193], 0
	v_mfma_f32_16x16x32_bf16 v[104:107], v[158:161], v[190:193], 0
	v_mfma_f32_16x16x32_bf16 v[92:95], v[150:153], v[198:201], 0
	v_mfma_f32_16x16x32_bf16 v[88:91], v[158:161], v[198:201], 0
	v_mfma_f32_16x16x32_bf16 v[76:79], v[150:153], v[206:209], 0
	v_mfma_f32_16x16x32_bf16 v[72:75], v[158:161], v[206:209], 0
	v_mfma_f32_16x16x32_bf16 v[124:127], v[154:157], v[186:189], v[124:127]
	v_mfma_f32_16x16x32_bf16 v[120:123], v[162:165], v[186:189], v[120:123]
	v_mfma_f32_16x16x32_bf16 v[108:111], v[154:157], v[194:197], v[108:111]
	v_mfma_f32_16x16x32_bf16 v[104:107], v[162:165], v[194:197], v[104:107]
	v_mfma_f32_16x16x32_bf16 v[92:95], v[154:157], v[202:205], v[92:95]
	v_mfma_f32_16x16x32_bf16 v[88:91], v[162:165], v[202:205], v[88:91]
	v_mfma_f32_16x16x32_bf16 v[76:79], v[154:157], v[210:213], v[76:79]
	v_mfma_f32_16x16x32_bf16 v[72:75], v[162:165], v[210:213], v[72:75]
	v_mfma_f32_16x16x32_bf16 v[116:119], v[166:169], v[182:185], 0
	v_mfma_f32_16x16x32_bf16 v[112:115], v[174:177], v[182:185], 0
	v_mfma_f32_16x16x32_bf16 v[100:103], v[166:169], v[190:193], 0
	v_mfma_f32_16x16x32_bf16 v[96:99], v[174:177], v[190:193], 0
	v_mfma_f32_16x16x32_bf16 v[84:87], v[166:169], v[198:201], 0
	v_mfma_f32_16x16x32_bf16 v[80:83], v[174:177], v[198:201], 0
	v_mfma_f32_16x16x32_bf16 v[68:71], v[166:169], v[206:209], 0
	v_mfma_f32_16x16x32_bf16 v[64:67], v[174:177], v[206:209], 0
	v_mfma_f32_16x16x32_bf16 v[116:119], v[170:173], v[186:189], v[116:119]
	v_mfma_f32_16x16x32_bf16 v[112:115], v[178:181], v[186:189], v[112:115]
	v_mfma_f32_16x16x32_bf16 v[100:103], v[170:173], v[194:197], v[100:103]
	v_mfma_f32_16x16x32_bf16 v[96:99], v[178:181], v[194:197], v[96:99]
	v_mfma_f32_16x16x32_bf16 v[84:87], v[170:173], v[202:205], v[84:87]
	v_mfma_f32_16x16x32_bf16 v[80:83], v[178:181], v[202:205], v[80:83]
	v_mfma_f32_16x16x32_bf16 v[68:71], v[170:173], v[210:213], v[68:71]
	v_mfma_f32_16x16x32_bf16 v[64:67], v[178:181], v[210:213], v[64:67]
	s_barrier
	s_mov_b32 m0, s93
	s_add_u32 s98, s52, 0x80
	s_addc_u32 s99, s53, 0
	ds_read_b128 v[182:185], v146 offset:16384
	ds_read_b128 v[186:189], v146 offset:17408
	ds_read_b128 v[190:193], v146 offset:18432
	ds_read_b128 v[194:197], v146 offset:19456
	ds_read_b128 v[198:201], v146 offset:20480
	ds_read_b128 v[202:205], v146 offset:21504
	ds_read_b128 v[206:209], v146 offset:22528
	ds_read_b128 v[210:213], v146 offset:23552
	global_load_lds_dwordx4 v130, s[52:53]
	s_mov_b32 m0, s90
	s_nop 0
	global_load_lds_dwordx4 v128, s[52:53]
	s_mov_b32 m0, s92
	s_add_u32 s100, s50, 0x80
	s_addc_u32 s101, s51, 0
	global_load_lds_dwordx4 v130, s[54:55]
	s_mov_b32 m0, s91
	s_nop 0
	global_load_lds_dwordx4 v128, s[54:55]
	s_mov_b32 m0, s61
	s_nop 0
	global_load_lds_dwordx4 v130, s[50:51]
	s_mov_b32 m0, s62
	s_nop 0
	global_load_lds_dwordx4 v128, s[50:51]
	s_waitcnt vmcnt(8)
	s_waitcnt lgkmcnt(0)
	s_barrier
	v_mfma_f32_16x16x32_bf16 v[60:63], v[150:153], v[182:185], 0
	v_mfma_f32_16x16x32_bf16 v[56:59], v[158:161], v[182:185], 0
	v_mfma_f32_16x16x32_bf16 v[44:47], v[150:153], v[190:193], 0
	v_mfma_f32_16x16x32_bf16 v[40:43], v[158:161], v[190:193], 0
	v_mfma_f32_16x16x32_bf16 v[28:31], v[150:153], v[198:201], 0
	v_mfma_f32_16x16x32_bf16 v[24:27], v[158:161], v[198:201], 0
	v_mfma_f32_16x16x32_bf16 v[12:15], v[150:153], v[206:209], 0
	v_mfma_f32_16x16x32_bf16 v[8:11], v[158:161], v[206:209], 0
	v_mfma_f32_16x16x32_bf16 v[60:63], v[154:157], v[186:189], v[60:63]
	v_mfma_f32_16x16x32_bf16 v[56:59], v[162:165], v[186:189], v[56:59]
	v_mfma_f32_16x16x32_bf16 v[44:47], v[154:157], v[194:197], v[44:47]
	v_mfma_f32_16x16x32_bf16 v[40:43], v[162:165], v[194:197], v[40:43]
	v_mfma_f32_16x16x32_bf16 v[28:31], v[154:157], v[202:205], v[28:31]
	v_mfma_f32_16x16x32_bf16 v[24:27], v[162:165], v[202:205], v[24:27]
	v_mfma_f32_16x16x32_bf16 v[12:15], v[154:157], v[210:213], v[12:15]
	v_mfma_f32_16x16x32_bf16 v[8:11], v[162:165], v[210:213], v[8:11]
	v_mfma_f32_16x16x32_bf16 v[52:55], v[166:169], v[182:185], 0
	v_mfma_f32_16x16x32_bf16 v[48:51], v[174:177], v[182:185], 0
	v_mfma_f32_16x16x32_bf16 v[36:39], v[166:169], v[190:193], 0
	v_mfma_f32_16x16x32_bf16 v[32:35], v[174:177], v[190:193], 0
	v_mfma_f32_16x16x32_bf16 v[20:23], v[166:169], v[198:201], 0
	v_mfma_f32_16x16x32_bf16 v[16:19], v[174:177], v[198:201], 0
	v_mfma_f32_16x16x32_bf16 v[4:7], v[166:169], v[206:209], 0
	v_mfma_f32_16x16x32_bf16 v[0:3], v[174:177], v[206:209], 0
	v_mfma_f32_16x16x32_bf16 v[52:55], v[170:173], v[186:189], v[52:55]
	v_mfma_f32_16x16x32_bf16 v[48:51], v[178:181], v[186:189], v[48:51]
	v_mfma_f32_16x16x32_bf16 v[36:39], v[170:173], v[194:197], v[36:39]
	v_mfma_f32_16x16x32_bf16 v[32:35], v[178:181], v[194:197], v[32:35]
	v_mfma_f32_16x16x32_bf16 v[20:23], v[170:173], v[202:205], v[20:23]
	v_mfma_f32_16x16x32_bf16 v[16:19], v[178:181], v[202:205], v[16:19]
	v_mfma_f32_16x16x32_bf16 v[4:7], v[170:173], v[210:213], v[4:7]
	v_mfma_f32_16x16x32_bf16 v[0:3], v[178:181], v[210:213], v[0:3]
	s_barrier
	v_add_u32_e32 v132, s89, v143
	ds_read_b128 v[150:153], v132
	ds_read_b128 v[154:157], v132 offset:1024
	ds_read_b128 v[158:161], v132 offset:2048
	ds_read_b128 v[162:165], v132 offset:3072
	v_add_u32_e32 v132, s88, v143
	ds_read_b128 v[166:169], v132
	ds_read_b128 v[170:173], v132 offset:1024
	ds_read_b128 v[174:177], v132 offset:2048
	ds_read_b128 v[178:181], v132 offset:3072
	s_mov_b32 m0, s63
	ds_read_b128 v[182:185], v146 offset:32768
	ds_read_b128 v[186:189], v146 offset:33792
	ds_read_b128 v[190:193], v146 offset:34816
	ds_read_b128 v[194:197], v146 offset:35840
	ds_read_b128 v[198:201], v146 offset:36864
	ds_read_b128 v[202:205], v146 offset:37888
	ds_read_b128 v[206:209], v146 offset:38912
	ds_read_b128 v[210:213], v146 offset:39936
	global_load_lds_dwordx4 v130, s[48:49]
	s_mov_b32 m0, s64
	s_nop 0
	global_load_lds_dwordx4 v128, s[48:49]
	s_waitcnt vmcnt(8)
	s_waitcnt lgkmcnt(0)
	s_barrier
	v_mfma_f32_16x16x32_bf16 v[124:127], v[150:153], v[182:185], v[124:127]
	v_mfma_f32_16x16x32_bf16 v[120:123], v[158:161], v[182:185], v[120:123]
	v_mfma_f32_16x16x32_bf16 v[108:111], v[150:153], v[190:193], v[108:111]
	v_mfma_f32_16x16x32_bf16 v[104:107], v[158:161], v[190:193], v[104:107]
	v_mfma_f32_16x16x32_bf16 v[92:95], v[150:153], v[198:201], v[92:95]
	v_mfma_f32_16x16x32_bf16 v[88:91], v[158:161], v[198:201], v[88:91]
	v_mfma_f32_16x16x32_bf16 v[76:79], v[150:153], v[206:209], v[76:79]
	v_mfma_f32_16x16x32_bf16 v[72:75], v[158:161], v[206:209], v[72:75]
	v_mfma_f32_16x16x32_bf16 v[124:127], v[154:157], v[186:189], v[124:127]
	v_mfma_f32_16x16x32_bf16 v[120:123], v[162:165], v[186:189], v[120:123]
	v_mfma_f32_16x16x32_bf16 v[108:111], v[154:157], v[194:197], v[108:111]
	v_mfma_f32_16x16x32_bf16 v[104:107], v[162:165], v[194:197], v[104:107]
	v_mfma_f32_16x16x32_bf16 v[92:95], v[154:157], v[202:205], v[92:95]
	v_mfma_f32_16x16x32_bf16 v[88:91], v[162:165], v[202:205], v[88:91]
	v_mfma_f32_16x16x32_bf16 v[76:79], v[154:157], v[210:213], v[76:79]
	v_mfma_f32_16x16x32_bf16 v[72:75], v[162:165], v[210:213], v[72:75]
	v_mfma_f32_16x16x32_bf16 v[116:119], v[166:169], v[182:185], v[116:119]
	v_mfma_f32_16x16x32_bf16 v[112:115], v[174:177], v[182:185], v[112:115]
	v_mfma_f32_16x16x32_bf16 v[100:103], v[166:169], v[190:193], v[100:103]
	v_mfma_f32_16x16x32_bf16 v[96:99], v[174:177], v[190:193], v[96:99]
	v_mfma_f32_16x16x32_bf16 v[84:87], v[166:169], v[198:201], v[84:87]
	v_mfma_f32_16x16x32_bf16 v[80:83], v[174:177], v[198:201], v[80:83]
	v_mfma_f32_16x16x32_bf16 v[68:71], v[166:169], v[206:209], v[68:71]
	v_mfma_f32_16x16x32_bf16 v[64:67], v[174:177], v[206:209], v[64:67]
	v_mfma_f32_16x16x32_bf16 v[116:119], v[170:173], v[186:189], v[116:119]
	v_mfma_f32_16x16x32_bf16 v[112:115], v[178:181], v[186:189], v[112:115]
	v_mfma_f32_16x16x32_bf16 v[100:103], v[170:173], v[194:197], v[100:103]
	v_mfma_f32_16x16x32_bf16 v[96:99], v[178:181], v[194:197], v[96:99]
	v_mfma_f32_16x16x32_bf16 v[84:87], v[170:173], v[202:205], v[84:87]
	v_mfma_f32_16x16x32_bf16 v[80:83], v[178:181], v[202:205], v[80:83]
	v_mfma_f32_16x16x32_bf16 v[68:71], v[170:173], v[210:213], v[68:71]
	v_mfma_f32_16x16x32_bf16 v[64:67], v[178:181], v[210:213], v[64:67]
	s_barrier
	s_mov_b32 m0, s87
	ds_read_b128 v[182:185], v146 offset:49152
	ds_read_b128 v[186:189], v146 offset:50176
	ds_read_b128 v[190:193], v146 offset:51200
	ds_read_b128 v[194:197], v146 offset:52224
	ds_read_b128 v[198:201], v146 offset:53248
	ds_read_b128 v[202:205], v146 offset:54272
	ds_read_b128 v[206:209], v146 offset:55296
	ds_read_b128 v[210:213], v146 offset:56320
	global_load_lds_dwordx4 v130, s[98:99]
	s_mov_b32 m0, s85
	s_nop 0
	global_load_lds_dwordx4 v128, s[98:99]
	s_mov_b32 m0, s86
	s_nop 0
	global_load_lds_dwordx4 v130, s[46:47]
	s_mov_b32 m0, s84
	s_nop 0
	global_load_lds_dwordx4 v128, s[46:47]
	s_mov_b32 m0, s70
	s_nop 0
	global_load_lds_dwordx4 v130, s[100:101]
	s_mov_b32 m0, s71
	s_nop 0
	global_load_lds_dwordx4 v128, s[100:101]
	s_waitcnt vmcnt(8)
	s_waitcnt lgkmcnt(0)
	s_barrier
	v_mfma_f32_16x16x32_bf16 v[60:63], v[150:153], v[182:185], v[60:63]
	v_mfma_f32_16x16x32_bf16 v[56:59], v[158:161], v[182:185], v[56:59]
	v_mfma_f32_16x16x32_bf16 v[44:47], v[150:153], v[190:193], v[44:47]
	v_mfma_f32_16x16x32_bf16 v[40:43], v[158:161], v[190:193], v[40:43]
	v_mfma_f32_16x16x32_bf16 v[28:31], v[150:153], v[198:201], v[28:31]
	v_mfma_f32_16x16x32_bf16 v[24:27], v[158:161], v[198:201], v[24:27]
	v_mfma_f32_16x16x32_bf16 v[12:15], v[150:153], v[206:209], v[12:15]
	v_mfma_f32_16x16x32_bf16 v[8:11], v[158:161], v[206:209], v[8:11]
	v_mfma_f32_16x16x32_bf16 v[60:63], v[154:157], v[186:189], v[60:63]
	v_mfma_f32_16x16x32_bf16 v[56:59], v[162:165], v[186:189], v[56:59]
	v_mfma_f32_16x16x32_bf16 v[44:47], v[154:157], v[194:197], v[44:47]
	v_mfma_f32_16x16x32_bf16 v[40:43], v[162:165], v[194:197], v[40:43]
	v_mfma_f32_16x16x32_bf16 v[28:31], v[154:157], v[202:205], v[28:31]
	v_mfma_f32_16x16x32_bf16 v[24:27], v[162:165], v[202:205], v[24:27]
	v_mfma_f32_16x16x32_bf16 v[12:15], v[154:157], v[210:213], v[12:15]
	v_mfma_f32_16x16x32_bf16 v[8:11], v[162:165], v[210:213], v[8:11]
	v_mfma_f32_16x16x32_bf16 v[52:55], v[166:169], v[182:185], v[52:55]
	v_mfma_f32_16x16x32_bf16 v[48:51], v[174:177], v[182:185], v[48:51]
	v_mfma_f32_16x16x32_bf16 v[36:39], v[166:169], v[190:193], v[36:39]
	v_mfma_f32_16x16x32_bf16 v[32:35], v[174:177], v[190:193], v[32:35]
	v_mfma_f32_16x16x32_bf16 v[20:23], v[166:169], v[198:201], v[20:23]
	v_mfma_f32_16x16x32_bf16 v[16:19], v[174:177], v[198:201], v[16:19]
	v_mfma_f32_16x16x32_bf16 v[4:7], v[166:169], v[206:209], v[4:7]
	v_mfma_f32_16x16x32_bf16 v[0:3], v[174:177], v[206:209], v[0:3]
	v_mfma_f32_16x16x32_bf16 v[52:55], v[170:173], v[186:189], v[52:55]
	v_mfma_f32_16x16x32_bf16 v[48:51], v[178:181], v[186:189], v[48:51]
	v_mfma_f32_16x16x32_bf16 v[36:39], v[170:173], v[194:197], v[36:39]
	v_mfma_f32_16x16x32_bf16 v[32:35], v[178:181], v[194:197], v[32:35]
	v_mfma_f32_16x16x32_bf16 v[20:23], v[170:173], v[202:205], v[20:23]
	v_mfma_f32_16x16x32_bf16 v[16:19], v[178:181], v[202:205], v[16:19]
	v_mfma_f32_16x16x32_bf16 v[4:7], v[170:173], v[210:213], v[4:7]
	v_mfma_f32_16x16x32_bf16 v[0:3], v[178:181], v[210:213], v[0:3]
	s_barrier
	s_andn2_b64 vcc, exec, s[44:45]
	s_mov_b64 s[46:47], -1
	s_mov_b64 s[44:45], 0
	s_mov_b64 s[48:49], 0x100
	s_cbranch_vccnz .Lkx_744
.LBB0_744:
	s_add_u32 s54, s42, s48
	s_addc_u32 s55, s43, s49
	s_add_u32 s52, s54, 0x100
	s_addc_u32 s53, s55, 0
	s_and_b64 s[50:51], s[46:47], exec
	s_cselect_b32 s51, s35, s53
	s_cselect_b32 s50, s82, s52
	s_add_u32 s48, s40, s48
	s_addc_u32 s49, s41, s49
	s_add_u32 s48, s48, 0x100
	s_addc_u32 s49, s49, 0
	s_and_b64 s[46:47], s[46:47], exec
	s_cselect_b32 s53, s31, s49
	s_cselect_b32 s52, s83, s48
	s_cselect_b32 s98, 1, 0
	s_add_u32 s56, s54, 0x10080
	ds_read_b128 v[150:153], v144
	ds_read_b128 v[154:157], v144 offset:1024
	ds_read_b128 v[158:161], v144 offset:2048
	ds_read_b128 v[162:165], v144 offset:3072
	ds_read_b128 v[166:169], v145
	ds_read_b128 v[170:173], v145 offset:1024
	ds_read_b128 v[174:177], v145 offset:2048
	ds_read_b128 v[178:181], v145 offset:3072
	s_addc_u32 s57, s55, 0
	s_add_i32 s93, s74, s60
	s_add_i32 m0, s61, 0xc000
	s_add_i32 s94, s61, 0xe000
	s_add_i32 s90, s93, 0x2000
	s_add_u32 s54, s52, 0x10000
	s_addc_u32 s55, s53, 0
	s_add_i32 s92, s75, s60
	s_add_i32 s91, s92, 0x2000
	s_add_i32 s89, 0, 0x18000
	s_add_i32 s88, 0, 0x1c000
	s_add_u32 s48, s50, 0x10000
	s_addc_u32 s49, s51, 0
	s_add_i32 s87, s89, s60
	s_add_i32 s85, s87, 0x2000
	s_add_u32 s46, s52, 0x10080
	s_addc_u32 s47, s53, 0
	s_add_i32 s86, s88, s60
	s_add_i32 s84, s86, 0x2000
	ds_read_b128 v[182:185], v146
	ds_read_b128 v[186:189], v146 offset:1024
	ds_read_b128 v[190:193], v146 offset:2048
	ds_read_b128 v[194:197], v146 offset:3072
	ds_read_b128 v[198:201], v146 offset:4096
	ds_read_b128 v[202:205], v146 offset:5120
	ds_read_b128 v[206:209], v146 offset:6144
	ds_read_b128 v[210:213], v146 offset:7168
	global_load_lds_dwordx4 v130, s[56:57]
	s_mov_b32 m0, s94
	s_nop 0
	global_load_lds_dwordx4 v128, s[56:57]
	s_waitcnt vmcnt(8)
	s_waitcnt lgkmcnt(0)
	s_cmp_lg_u32 s98, 0
	s_cbranch_scc0 .Lkv_nopf
	v_lshl_add_u32 v138, s18, 8, v141
	v_ashrrev_i32_e32 v139, 31, v138
	v_lshl_add_u64 v[138:139], v[138:139], 4, s[14:15]
	global_load_dwordx4 v[222:225], v[138:139], off
	global_load_dwordx4 v[226:229], v[138:139], off offset:256
	global_load_dwordx4 v[230:233], v[138:139], off offset:512
	global_load_dwordx4 v[234:237], v[138:139], off offset:768
	global_load_dwordx4 v[238:241], v[138:139], off offset:2048
	global_load_dwordx4 v[242:245], v[138:139], off offset:2304
	global_load_dwordx4 v[248:251], v[138:139], off offset:2560
	global_load_dwordx4 v[252:255], v[138:139], off offset:2816
.Lkv_nopf:
	s_barrier
	v_mfma_f32_16x16x32_bf16 v[124:127], v[150:153], v[182:185], v[124:127]
	v_mfma_f32_16x16x32_bf16 v[120:123], v[158:161], v[182:185], v[120:123]
	v_mfma_f32_16x16x32_bf16 v[108:111], v[150:153], v[190:193], v[108:111]
	v_mfma_f32_16x16x32_bf16 v[104:107], v[158:161], v[190:193], v[104:107]
	v_mfma_f32_16x16x32_bf16 v[92:95], v[150:153], v[198:201], v[92:95]
	v_mfma_f32_16x16x32_bf16 v[88:91], v[158:161], v[198:201], v[88:91]
	v_mfma_f32_16x16x32_bf16 v[76:79], v[150:153], v[206:209], v[76:79]
	v_mfma_f32_16x16x32_bf16 v[72:75], v[158:161], v[206:209], v[72:75]
	v_mfma_f32_16x16x32_bf16 v[124:127], v[154:157], v[186:189], v[124:127]
	v_mfma_f32_16x16x32_bf16 v[120:123], v[162:165], v[186:189], v[120:123]
	v_mfma_f32_16x16x32_bf16 v[108:111], v[154:157], v[194:197], v[108:111]
	v_mfma_f32_16x16x32_bf16 v[104:107], v[162:165], v[194:197], v[104:107]
	v_mfma_f32_16x16x32_bf16 v[92:95], v[154:157], v[202:205], v[92:95]
	v_mfma_f32_16x16x32_bf16 v[88:91], v[162:165], v[202:205], v[88:91]
	v_mfma_f32_16x16x32_bf16 v[76:79], v[154:157], v[210:213], v[76:79]
	v_mfma_f32_16x16x32_bf16 v[72:75], v[162:165], v[210:213], v[72:75]
	v_mfma_f32_16x16x32_bf16 v[116:119], v[166:169], v[182:185], v[116:119]
	v_mfma_f32_16x16x32_bf16 v[112:115], v[174:177], v[182:185], v[112:115]
	v_mfma_f32_16x16x32_bf16 v[100:103], v[166:169], v[190:193], v[100:103]
	v_mfma_f32_16x16x32_bf16 v[96:99], v[174:177], v[190:193], v[96:99]
	v_mfma_f32_16x16x32_bf16 v[84:87], v[166:169], v[198:201], v[84:87]
	v_mfma_f32_16x16x32_bf16 v[80:83], v[174:177], v[198:201], v[80:83]
	v_mfma_f32_16x16x32_bf16 v[68:71], v[166:169], v[206:209], v[68:71]
	v_mfma_f32_16x16x32_bf16 v[64:67], v[174:177], v[206:209], v[64:67]
	v_mfma_f32_16x16x32_bf16 v[116:119], v[170:173], v[186:189], v[116:119]
	v_mfma_f32_16x16x32_bf16 v[112:115], v[178:181], v[186:189], v[112:115]
	v_mfma_f32_16x16x32_bf16 v[100:103], v[170:173], v[194:197], v[100:103]
	v_mfma_f32_16x16x32_bf16 v[96:99], v[178:181], v[194:197], v[96:99]
	v_mfma_f32_16x16x32_bf16 v[84:87], v[170:173], v[202:205], v[84:87]
	v_mfma_f32_16x16x32_bf16 v[80:83], v[178:181], v[202:205], v[80:83]
	v_mfma_f32_16x16x32_bf16 v[68:71], v[170:173], v[210:213], v[68:71]
	v_mfma_f32_16x16x32_bf16 v[64:67], v[178:181], v[210:213], v[64:67]
	s_barrier
	s_mov_b32 m0, s93
	s_add_u32 s98, s52, 0x80
	s_addc_u32 s99, s53, 0
	ds_read_b128 v[182:185], v146 offset:16384
	ds_read_b128 v[186:189], v146 offset:17408
	ds_read_b128 v[190:193], v146 offset:18432
	ds_read_b128 v[194:197], v146 offset:19456
	ds_read_b128 v[198:201], v146 offset:20480
	ds_read_b128 v[202:205], v146 offset:21504
	ds_read_b128 v[206:209], v146 offset:22528
	ds_read_b128 v[210:213], v146 offset:23552
	global_load_lds_dwordx4 v130, s[52:53]
	s_mov_b32 m0, s90
	s_nop 0
	global_load_lds_dwordx4 v128, s[52:53]
	s_mov_b32 m0, s92
	s_add_u32 s100, s50, 0x80
	s_addc_u32 s101, s51, 0
	global_load_lds_dwordx4 v130, s[54:55]
	s_mov_b32 m0, s91
	s_nop 0
	global_load_lds_dwordx4 v128, s[54:55]
	s_mov_b32 m0, s61
	s_nop 0
	global_load_lds_dwordx4 v130, s[50:51]
	s_mov_b32 m0, s62
	s_nop 0
	global_load_lds_dwordx4 v128, s[50:51]
	s_waitcnt vmcnt(8)
	s_waitcnt lgkmcnt(0)
	s_barrier
	v_mfma_f32_16x16x32_bf16 v[60:63], v[150:153], v[182:185], v[60:63]
	v_mfma_f32_16x16x32_bf16 v[56:59], v[158:161], v[182:185], v[56:59]
	v_mfma_f32_16x16x32_bf16 v[44:47], v[150:153], v[190:193], v[44:47]
	v_mfma_f32_16x16x32_bf16 v[40:43], v[158:161], v[190:193], v[40:43]
	v_mfma_f32_16x16x32_bf16 v[28:31], v[150:153], v[198:201], v[28:31]
	v_mfma_f32_16x16x32_bf16 v[24:27], v[158:161], v[198:201], v[24:27]
	v_mfma_f32_16x16x32_bf16 v[12:15], v[150:153], v[206:209], v[12:15]
	v_mfma_f32_16x16x32_bf16 v[8:11], v[158:161], v[206:209], v[8:11]
	v_mfma_f32_16x16x32_bf16 v[60:63], v[154:157], v[186:189], v[60:63]
	v_mfma_f32_16x16x32_bf16 v[56:59], v[162:165], v[186:189], v[56:59]
	v_mfma_f32_16x16x32_bf16 v[44:47], v[154:157], v[194:197], v[44:47]
	v_mfma_f32_16x16x32_bf16 v[40:43], v[162:165], v[194:197], v[40:43]
	v_mfma_f32_16x16x32_bf16 v[28:31], v[154:157], v[202:205], v[28:31]
	v_mfma_f32_16x16x32_bf16 v[24:27], v[162:165], v[202:205], v[24:27]
	v_mfma_f32_16x16x32_bf16 v[12:15], v[154:157], v[210:213], v[12:15]
	v_mfma_f32_16x16x32_bf16 v[8:11], v[162:165], v[210:213], v[8:11]
	v_mfma_f32_16x16x32_bf16 v[52:55], v[166:169], v[182:185], v[52:55]
	v_mfma_f32_16x16x32_bf16 v[48:51], v[174:177], v[182:185], v[48:51]
	v_mfma_f32_16x16x32_bf16 v[36:39], v[166:169], v[190:193], v[36:39]
	v_mfma_f32_16x16x32_bf16 v[32:35], v[174:177], v[190:193], v[32:35]
	v_mfma_f32_16x16x32_bf16 v[20:23], v[166:169], v[198:201], v[20:23]
	v_mfma_f32_16x16x32_bf16 v[16:19], v[174:177], v[198:201], v[16:19]
	v_mfma_f32_16x16x32_bf16 v[4:7], v[166:169], v[206:209], v[4:7]
	v_mfma_f32_16x16x32_bf16 v[0:3], v[174:177], v[206:209], v[0:3]
	v_mfma_f32_16x16x32_bf16 v[52:55], v[170:173], v[186:189], v[52:55]
	v_mfma_f32_16x16x32_bf16 v[48:51], v[178:181], v[186:189], v[48:51]
	v_mfma_f32_16x16x32_bf16 v[36:39], v[170:173], v[194:197], v[36:39]
	v_mfma_f32_16x16x32_bf16 v[32:35], v[178:181], v[194:197], v[32:35]
	v_mfma_f32_16x16x32_bf16 v[20:23], v[170:173], v[202:205], v[20:23]
	v_mfma_f32_16x16x32_bf16 v[16:19], v[178:181], v[202:205], v[16:19]
	v_mfma_f32_16x16x32_bf16 v[4:7], v[170:173], v[210:213], v[4:7]
	v_mfma_f32_16x16x32_bf16 v[0:3], v[178:181], v[210:213], v[0:3]
	s_barrier
	v_add_u32_e32 v132, s89, v143
	ds_read_b128 v[150:153], v132
	ds_read_b128 v[154:157], v132 offset:1024
	ds_read_b128 v[158:161], v132 offset:2048
	ds_read_b128 v[162:165], v132 offset:3072
	v_add_u32_e32 v132, s88, v143
	ds_read_b128 v[166:169], v132
	ds_read_b128 v[170:173], v132 offset:1024
	ds_read_b128 v[174:177], v132 offset:2048
	ds_read_b128 v[178:181], v132 offset:3072
	s_mov_b32 m0, s63
	ds_read_b128 v[182:185], v146 offset:32768
	ds_read_b128 v[186:189], v146 offset:33792
	ds_read_b128 v[190:193], v146 offset:34816
	ds_read_b128 v[194:197], v146 offset:35840
	ds_read_b128 v[198:201], v146 offset:36864
	ds_read_b128 v[202:205], v146 offset:37888
	ds_read_b128 v[206:209], v146 offset:38912
	ds_read_b128 v[210:213], v146 offset:39936
	global_load_lds_dwordx4 v130, s[48:49]
	s_mov_b32 m0, s64
	s_nop 0
	global_load_lds_dwordx4 v128, s[48:49]
	s_waitcnt vmcnt(8)
	s_waitcnt lgkmcnt(0)
	s_barrier
	v_mfma_f32_16x16x32_bf16 v[124:127], v[150:153], v[182:185], v[124:127]
	v_mfma_f32_16x16x32_bf16 v[120:123], v[158:161], v[182:185], v[120:123]
	v_mfma_f32_16x16x32_bf16 v[108:111], v[150:153], v[190:193], v[108:111]
	v_mfma_f32_16x16x32_bf16 v[104:107], v[158:161], v[190:193], v[104:107]
	v_mfma_f32_16x16x32_bf16 v[92:95], v[150:153], v[198:201], v[92:95]
	v_mfma_f32_16x16x32_bf16 v[88:91], v[158:161], v[198:201], v[88:91]
	v_mfma_f32_16x16x32_bf16 v[76:79], v[150:153], v[206:209], v[76:79]
	v_mfma_f32_16x16x32_bf16 v[72:75], v[158:161], v[206:209], v[72:75]
	v_mfma_f32_16x16x32_bf16 v[124:127], v[154:157], v[186:189], v[124:127]
	v_mfma_f32_16x16x32_bf16 v[120:123], v[162:165], v[186:189], v[120:123]
	v_mfma_f32_16x16x32_bf16 v[108:111], v[154:157], v[194:197], v[108:111]
	v_mfma_f32_16x16x32_bf16 v[104:107], v[162:165], v[194:197], v[104:107]
	v_mfma_f32_16x16x32_bf16 v[92:95], v[154:157], v[202:205], v[92:95]
	v_mfma_f32_16x16x32_bf16 v[88:91], v[162:165], v[202:205], v[88:91]
	v_mfma_f32_16x16x32_bf16 v[76:79], v[154:157], v[210:213], v[76:79]
	v_mfma_f32_16x16x32_bf16 v[72:75], v[162:165], v[210:213], v[72:75]
	v_mfma_f32_16x16x32_bf16 v[116:119], v[166:169], v[182:185], v[116:119]
	v_mfma_f32_16x16x32_bf16 v[112:115], v[174:177], v[182:185], v[112:115]
	v_mfma_f32_16x16x32_bf16 v[100:103], v[166:169], v[190:193], v[100:103]
	v_mfma_f32_16x16x32_bf16 v[96:99], v[174:177], v[190:193], v[96:99]
	v_mfma_f32_16x16x32_bf16 v[84:87], v[166:169], v[198:201], v[84:87]
	v_mfma_f32_16x16x32_bf16 v[80:83], v[174:177], v[198:201], v[80:83]
	v_mfma_f32_16x16x32_bf16 v[68:71], v[166:169], v[206:209], v[68:71]
	v_mfma_f32_16x16x32_bf16 v[64:67], v[174:177], v[206:209], v[64:67]
	v_mfma_f32_16x16x32_bf16 v[116:119], v[170:173], v[186:189], v[116:119]
	v_mfma_f32_16x16x32_bf16 v[112:115], v[178:181], v[186:189], v[112:115]
	v_mfma_f32_16x16x32_bf16 v[100:103], v[170:173], v[194:197], v[100:103]
	v_mfma_f32_16x16x32_bf16 v[96:99], v[178:181], v[194:197], v[96:99]
	v_mfma_f32_16x16x32_bf16 v[84:87], v[170:173], v[202:205], v[84:87]
	v_mfma_f32_16x16x32_bf16 v[80:83], v[178:181], v[202:205], v[80:83]
	v_mfma_f32_16x16x32_bf16 v[68:71], v[170:173], v[210:213], v[68:71]
	v_mfma_f32_16x16x32_bf16 v[64:67], v[178:181], v[210:213], v[64:67]
	s_barrier
	s_mov_b32 m0, s87
	ds_read_b128 v[182:185], v146 offset:49152
	ds_read_b128 v[186:189], v146 offset:50176
	ds_read_b128 v[190:193], v146 offset:51200
	ds_read_b128 v[194:197], v146 offset:52224
	ds_read_b128 v[198:201], v146 offset:53248
	ds_read_b128 v[202:205], v146 offset:54272
	ds_read_b128 v[206:209], v146 offset:55296
	ds_read_b128 v[210:213], v146 offset:56320
	global_load_lds_dwordx4 v130, s[98:99]
	s_mov_b32 m0, s85
	s_nop 0
	global_load_lds_dwordx4 v128, s[98:99]
	s_mov_b32 m0, s86
	s_nop 0
	global_load_lds_dwordx4 v130, s[46:47]
	s_mov_b32 m0, s84
	s_nop 0
	global_load_lds_dwordx4 v128, s[46:47]
	s_mov_b32 m0, s70
	s_nop 0
	global_load_lds_dwordx4 v130, s[100:101]
	s_mov_b32 m0, s71
	s_nop 0
	global_load_lds_dwordx4 v128, s[100:101]
	s_waitcnt vmcnt(8)
	s_waitcnt lgkmcnt(0)
	s_barrier
	v_mfma_f32_16x16x32_bf16 v[60:63], v[150:153], v[182:185], v[60:63]
	v_mfma_f32_16x16x32_bf16 v[56:59], v[158:161], v[182:185], v[56:59]
	v_mfma_f32_16x16x32_bf16 v[44:47], v[150:153], v[190:193], v[44:47]
	v_mfma_f32_16x16x32_bf16 v[40:43], v[158:161], v[190:193], v[40:43]
	v_mfma_f32_16x16x32_bf16 v[28:31], v[150:153], v[198:201], v[28:31]
	v_mfma_f32_16x16x32_bf16 v[24:27], v[158:161], v[198:201], v[24:27]
	v_mfma_f32_16x16x32_bf16 v[12:15], v[150:153], v[206:209], v[12:15]
	v_mfma_f32_16x16x32_bf16 v[8:11], v[158:161], v[206:209], v[8:11]
	v_mfma_f32_16x16x32_bf16 v[60:63], v[154:157], v[186:189], v[60:63]
	v_mfma_f32_16x16x32_bf16 v[56:59], v[162:165], v[186:189], v[56:59]
	v_mfma_f32_16x16x32_bf16 v[44:47], v[154:157], v[194:197], v[44:47]
	v_mfma_f32_16x16x32_bf16 v[40:43], v[162:165], v[194:197], v[40:43]
	v_mfma_f32_16x16x32_bf16 v[28:31], v[154:157], v[202:205], v[28:31]
	v_mfma_f32_16x16x32_bf16 v[24:27], v[162:165], v[202:205], v[24:27]
	v_mfma_f32_16x16x32_bf16 v[12:15], v[154:157], v[210:213], v[12:15]
	v_mfma_f32_16x16x32_bf16 v[8:11], v[162:165], v[210:213], v[8:11]
	v_mfma_f32_16x16x32_bf16 v[52:55], v[166:169], v[182:185], v[52:55]
	v_mfma_f32_16x16x32_bf16 v[48:51], v[174:177], v[182:185], v[48:51]
	v_mfma_f32_16x16x32_bf16 v[36:39], v[166:169], v[190:193], v[36:39]
	v_mfma_f32_16x16x32_bf16 v[32:35], v[174:177], v[190:193], v[32:35]
	v_mfma_f32_16x16x32_bf16 v[20:23], v[166:169], v[198:201], v[20:23]
	v_mfma_f32_16x16x32_bf16 v[16:19], v[174:177], v[198:201], v[16:19]
	v_mfma_f32_16x16x32_bf16 v[4:7], v[166:169], v[206:209], v[4:7]
	v_mfma_f32_16x16x32_bf16 v[0:3], v[174:177], v[206:209], v[0:3]
	v_mfma_f32_16x16x32_bf16 v[52:55], v[170:173], v[186:189], v[52:55]
	v_mfma_f32_16x16x32_bf16 v[48:51], v[178:181], v[186:189], v[48:51]
	v_mfma_f32_16x16x32_bf16 v[36:39], v[170:173], v[194:197], v[36:39]
	v_mfma_f32_16x16x32_bf16 v[32:35], v[178:181], v[194:197], v[32:35]
	v_mfma_f32_16x16x32_bf16 v[20:23], v[170:173], v[202:205], v[20:23]
	v_mfma_f32_16x16x32_bf16 v[16:19], v[178:181], v[202:205], v[16:19]
	v_mfma_f32_16x16x32_bf16 v[4:7], v[170:173], v[210:213], v[4:7]
	v_mfma_f32_16x16x32_bf16 v[0:3], v[178:181], v[210:213], v[0:3]
	s_barrier
	s_andn2_b64 vcc, exec, s[44:45]
	s_mov_b64 s[46:47], -1
	s_mov_b64 s[44:45], 0
	s_mov_b64 s[48:49], 0x100
	s_cbranch_vccz .LBB0_744
